# attention loop: one barrier per KV tile (3-deep V ring in LDS, K/V LDS staging overlapped with QK MFMAs), softmax VALU spread under MFMAs
# speedup vs baseline: 1.0135x; 1.0135x over previous
.LBB0_725:
	s_ashr_i32 s42, s4, 8
	s_ashr_i32 s43, s42, 31
	s_lshl_b32 s10, s4, 8
	s_lshl_b64 s[46:47], s[42:43], 13
	s_and_b32 s10, s10, 0x1f00
	s_or_b32 s46, s46, s10
	s_lshl_b32 s2, s4, 1
	s_mul_i32 s10, s47, 0xc00
	s_mul_hi_u32 s11, s46, 0xc00
	s_and_b32 s2, s2, 0x100
	s_bfe_u32 s3, s4, 0x30005
	s_add_i32 s11, s11, s10
	s_mul_i32 s10, s46, 0xc00
	s_add_u32 s16, s6, s10
	s_addc_u32 s11, s7, s11
	s_lshl_b32 s10, s3, 7
	s_lshl_b32 s3, s3, 8
	s_add_u32 s18, s16, s3
	s_addc_u32 s19, s11, 0
	s_mul_i32 s11, s42, 0x1800000
	s_mul_hi_i32 s3, s42, 0x1800000
	s_add_u32 s11, s6, s11
	s_addc_u32 s3, s7, s3
	s_and_b32 s16, s4, 0x80
	s_lshl_b32 s16, s16, 1
	s_add_u32 s40, s11, s16
	v_mov_b32_e32 v48, v192
	s_addc_u32 s41, s3, 0
	s_barrier
	s_add_i32 s3, 0, 0x10000
	v_and_b32_e32 v0, 0x3fffffc0, v48
	v_lshl_add_u32 v177, v0, 2, s3
	v_ashrrev_i32_e32 v0, 1, v48
	s_movk_i32 s3, 0xffe0
	v_bfe_u32 v181, v48, 5, 1
	v_and_b32_e32 v176, 0xffffffe0, v0
	v_bfi_b32 v2, s3, v0, v48
	v_mov_b64_e32 v[0:1], s[18:19]
	s_movk_i32 s20, 0xc00
	v_mad_i64_i32 v[0:1], s[18:19], v2, s20, v[0:1]
	v_lshlrev_b32_e32 v194, 4, v181
	v_lshl_add_u64 v[0:1], v[0:1], 0, v[194:195]
	v_ashrrev_i32_e32 v50, 4, v48
	global_load_dwordx4 v[124:127], v[0:1], off
	global_load_dwordx4 v[120:123], v[0:1], off offset:32
	global_load_dwordx4 v[116:119], v[0:1], off offset:64
	global_load_dwordx4 v[112:115], v[0:1], off offset:96
	global_load_dwordx4 v[108:111], v[0:1], off offset:128
	global_load_dwordx4 v[104:107], v[0:1], off offset:160
	global_load_dwordx4 v[100:103], v[0:1], off offset:192
	global_load_dwordx4 v[96:99], v[0:1], off offset:224
	v_and_b32_e32 v1, 0xfffff0, v50
	v_lshlrev_b32_e32 v2, 1, v50
	v_lshlrev_b32_e32 v0, 3, v48
	v_and_or_b32 v1, v2, 8, v1
	v_and_b32_e32 v52, 0x78, v0
	v_lshrrev_b32_e32 v2, 1, v50
	v_lshrrev_b32_e32 v1, 1, v1
	v_bfe_u32 v0, v0, 5, 2
	v_and_b32_e32 v3, 3, v50
	v_or_b32_e32 v1, v1, v0
	v_and_or_b32 v2, v2, 4, v3
	v_lshlrev_b32_e32 v16, 1, v52
	v_lshlrev_b32_e32 v1, 9, v1
	v_lshlrev_b32_e32 v2, 6, v2
	v_and_b32_e32 v3, 48, v16
	v_add_u32_e32 v18, 32, v50
	v_or3_b32 v17, v1, v2, v3
	v_and_b32_e32 v1, 0xfffff0, v18
	v_lshlrev_b32_e32 v4, 1, v18
	v_and_or_b32 v1, v4, 8, v1
	v_lshrrev_b32_e32 v1, 1, v1
	v_or_b32_e32 v0, v1, v0
	v_and_b32_e32 v49, 63, v48
	v_lshlrev_b32_e32 v0, 9, v0
	v_lshlrev_b32_e32 v20, 4, v48
	v_or3_b32 v19, v0, v2, v3
	v_lshlrev_b32_e32 v0, 3, v49
	v_and_b32_e32 v1, 0xc0, v20
	v_lshlrev_b32_e32 v2, 1, v48
	v_and_or_b32 v1, v0, 24, v1
	v_and_b32_e32 v2, 32, v2
	v_and_b32_e32 v0, 0x100, v0
	s_movk_i32 s16, 0x600
	v_or3_b32 v51, v1, v2, v0
	v_mad_i64_i32 v[0:1], s[18:19], v50, s16, 0
	v_or_b32_e32 v0, v0, v52
	v_lshl_add_u64 v[8:9], v[0:1], 1, s[40:41]
	global_load_dwordx4 v[0:3], v[8:9], off offset:2560
	v_mad_i64_i32 v[4:5], s[18:19], v18, s16, 0
	v_or_b32_e32 v4, v4, v52
	v_lshl_add_u64 v[12:13], v[4:5], 1, s[40:41]
	global_load_dwordx4 v[4:7], v[12:13], off offset:2560
	s_nop 0
	global_load_dwordx4 v[8:11], v[8:9], off offset:2048
	s_nop 0
	global_load_dwordx4 v[12:15], v[12:13], off offset:2048
	v_add_u32_e32 v183, 0, v17
	s_waitcnt vmcnt(0)
	v_and_b32_e32 v180, 31, v48
	v_lshlrev_b32_e32 v53, 8, v180
	v_and_b32_e32 v62, 0x70, v20
	v_add_u32_e32 v184, 0, v19
	v_or_b32_e32 v54, 32, v194
	v_bitop3_b32 v54, v54, v53, v62 bitop3:0xde
	v_add_u32_e32 v205, 0, v54
	s_cmp_lg_u32 0, -1
	s_cselect_b32 s3, 0, 0
	s_mov_b32 s53, s52
	s_mov_b32 s54, s52
	s_mov_b32 s55, s52
	s_mov_b32 s56, s52
	s_mov_b32 s57, s52
	s_mov_b32 s58, s52
	s_mov_b32 s59, s52
	s_mov_b32 s60, s52
	s_mov_b32 s61, s52
	s_mov_b32 s62, s52
	s_mov_b32 s63, s52
	s_mov_b32 s64, s52
	s_mov_b32 s65, s52
	s_mov_b32 s66, s52
	s_mov_b32 s67, s52
	v_add_u32_e32 v182, s3, v51
	s_mov_b32 s11, -1
	v_lshl_add_u32 v185, v180, 2, v177
	s_movk_i32 s15, 0xc00
	v_mov_b32_e32 v186, 0
	s_waitcnt vmcnt(3)
	ds_write_b128 v183, v[0:3]
	v_lshlrev_b32_e32 v0, 8, v50
	v_and_b32_e32 v1, 0x70, v48
	v_bitop3_b32 v0, v16, v0, v1 bitop3:0xde
	v_add_u32_e32 v188, 0, v0
	v_lshlrev_b32_e32 v0, 8, v18
	v_bitop3_b32 v0, v16, v0, v1 bitop3:0xde
	v_add_u32_e32 v189, 0, v0
	v_bitop3_b32 v0, v194, v53, v62 bitop3:0xde
	v_add_u32_e32 v190, 0, v0
	s_waitcnt vmcnt(2)
	ds_write_b128 v184, v[4:7]
	s_waitcnt vmcnt(1)
	ds_write_b128 v188, v[8:11] offset:32768
	s_waitcnt vmcnt(0)
	ds_write_b128 v189, v[12:15] offset:32768
	s_waitcnt lgkmcnt(0)
	s_barrier
	ds_read_b128 v[16:19], v190 offset:32768
	ds_read_b128 v[20:23], v190 offset:40960
	s_waitcnt lgkmcnt(1)
	v_mfma_f32_32x32x16_bf16 v[32:47], v[16:19], v[124:127], 0
	ds_read_b128 v[54:57], v205 offset:32768
	ds_read_b128 v[58:61], v205 offset:40960
	v_mov_b64_e32 v[0:1], s[52:53]
	v_mov_b64_e32 v[14:15], s[66:67]
	v_mov_b64_e32 v[2:3], s[54:55]
	v_mov_b64_e32 v[4:5], s[56:57]
	v_mov_b64_e32 v[6:7], s[58:59]
	v_mov_b64_e32 v[8:9], s[60:61]
	s_waitcnt lgkmcnt(2)
	v_mfma_f32_32x32x16_bf16 v[16:31], v[20:23], v[124:127], 0
	v_mov_b64_e32 v[10:11], s[62:63]
	v_mov_b64_e32 v[12:13], s[64:65]
	s_waitcnt lgkmcnt(1)
	v_mfma_f32_32x32x16_bf16 v[32:47], v[54:57], v[120:123], v[32:47]
	v_or_b32_e32 v54, 64, v194
	v_bitop3_b32 v54, v54, v53, v62 bitop3:0xde
	v_add_u32_e32 v204, 0, v54
	s_waitcnt lgkmcnt(0)
	v_mfma_f32_32x32x16_bf16 v[16:31], v[58:61], v[120:123], v[16:31]
	ds_read_b128 v[54:57], v204 offset:32768
	ds_read_b128 v[58:61], v204 offset:40960
	s_waitcnt lgkmcnt(1)
	v_mfma_f32_32x32x16_bf16 v[32:47], v[54:57], v[116:119], v[32:47]
	v_or_b32_e32 v54, 0x60, v194
	v_bitop3_b32 v54, v54, v53, v62 bitop3:0xde
	v_add_u32_e32 v202, 0, v54
	s_waitcnt lgkmcnt(0)
	v_mfma_f32_32x32x16_bf16 v[16:31], v[58:61], v[116:119], v[16:31]
	ds_read_b128 v[54:57], v202 offset:32768
	ds_read_b128 v[58:61], v202 offset:40960
	s_waitcnt lgkmcnt(1)
	v_mfma_f32_32x32x16_bf16 v[32:47], v[54:57], v[112:115], v[32:47]
	v_or_b32_e32 v54, 0x80, v194
	v_bitop3_b32 v54, v54, v53, v62 bitop3:0xde
	v_add_u32_e32 v191, 0, v54
	s_waitcnt lgkmcnt(0)
	v_mfma_f32_32x32x16_bf16 v[16:31], v[58:61], v[112:115], v[16:31]
	ds_read_b128 v[54:57], v191 offset:32768
	ds_read_b128 v[58:61], v191 offset:40960
	s_waitcnt lgkmcnt(1)
	v_mfma_f32_32x32x16_bf16 v[32:47], v[54:57], v[108:111], v[32:47]
	v_or_b32_e32 v54, 0xa0, v194
	v_bitop3_b32 v54, v54, v53, v62 bitop3:0xde
	v_add_u32_e32 v203, 0, v54
	s_waitcnt lgkmcnt(0)
	v_mfma_f32_32x32x16_bf16 v[16:31], v[58:61], v[108:111], v[16:31]
	ds_read_b128 v[54:57], v203 offset:32768
	ds_read_b128 v[58:61], v203 offset:40960
	s_waitcnt lgkmcnt(1)
	v_mfma_f32_32x32x16_bf16 v[32:47], v[54:57], v[104:107], v[32:47]
	v_or_b32_e32 v54, 0xc0, v194
	v_bitop3_b32 v54, v54, v53, v62 bitop3:0xde
	v_add_u32_e32 v206, 0, v54
	s_waitcnt lgkmcnt(0)
	v_mfma_f32_32x32x16_bf16 v[16:31], v[58:61], v[104:107], v[16:31]
	ds_read_b128 v[54:57], v206 offset:32768
	ds_read_b128 v[58:61], v206 offset:40960
	s_waitcnt lgkmcnt(1)
	v_mfma_f32_32x32x16_bf16 v[32:47], v[54:57], v[100:103], v[32:47]
	v_or_b32_e32 v54, 0xe0, v194
	v_bitop3_b32 v53, v54, v53, v62 bitop3:0xde
	v_add_u32_e32 v207, 0, v53
	s_waitcnt lgkmcnt(0)
	v_mfma_f32_32x32x16_bf16 v[16:31], v[58:61], v[100:103], v[16:31]
	ds_read_b128 v[54:57], v207 offset:32768
	ds_read_b128 v[58:61], v207 offset:40960
	s_waitcnt lgkmcnt(1)
	v_mfma_f32_32x32x16_bf16 v[32:47], v[54:57], v[96:99], v[32:47]
	v_mov_b32_e32 v55, 0xf149f2ca
	s_waitcnt lgkmcnt(0)
	v_mfma_f32_32x32x16_bf16 v[16:31], v[58:61], v[96:99], v[16:31]
	s_nop 8
	v_max_f32_e32 v53, v33, v33
	v_max_f32_e32 v54, v32, v32
	v_max_f32_e32 v53, v54, v53
	v_max3_f32 v53, v53, v34, v35
	v_max3_f32 v53, v53, v36, v37
	v_max3_f32 v53, v53, v38, v39
	v_max3_f32 v53, v53, v40, v41
	v_max3_f32 v53, v53, v42, v43
	v_max3_f32 v53, v53, v44, v45
	v_max3_f32 v53, v53, v46, v47
	v_max3_f32 v53, v53, v16, v17
	v_max3_f32 v53, v53, v18, v19
	v_max3_f32 v53, v53, v20, v21
	v_max3_f32 v53, v53, v22, v23
	v_max3_f32 v53, v53, v24, v25
	v_max3_f32 v53, v53, v26, v27
	v_max3_f32 v53, v53, v28, v29
	v_max3_f32 v53, v53, v30, v31
	v_mov_b32_e32 v54, v53
	s_nop 1
	v_permlane32_swap_b32_e32 v53, v54
	v_max_f32_e32 v54, v54, v54
	v_max_f32_e32 v53, v53, v53
	v_max_f32_e32 v53, v53, v54
	v_add_f32_e32 v54, 0x7149f2ca, v53
	v_max_f32_e32 v53, 0xf149f2ca, v53
	v_cmp_ge_f32_e32 vcc, s85, v54
	v_sub_f32_e32 v54, 0xf149f2ca, v53
	v_mul_f32_e32 v54, 0x3e0293ee, v54
	v_exp_f32_e32 v54, v54
	s_cmp_eq_u64 vcc, exec
	s_cselect_b64 vcc, -1, 0
	v_cndmask_b32_e32 v164, v53, v55, vcc
	v_cndmask_b32_e64 v208, v54, 1.0, vcc
	v_mul_f32_e32 v54, 0xbe0293ee, v164
	v_pk_fma_f32 v[148:149], v[20:21], s[12:13], v[54:55] op_sel_hi:[1,0,0]
	v_pk_fma_f32 v[156:157], v[16:17], s[12:13], v[54:55] op_sel_hi:[1,0,0]
	v_add_u32_e32 v16, 64, v50
	v_add_u32_e32 v20, 0x60, v50
	v_mad_i64_i32 v[16:17], s[18:19], v16, s16, 0
	v_mad_i64_i32 v[20:21], s[18:19], v20, s16, 0
	v_or_b32_e32 v16, v16, v52
	v_or_b32_e32 v20, v20, v52
	v_pk_fma_f32 v[152:153], v[28:29], s[12:13], v[54:55] op_sel_hi:[1,0,0]
	v_pk_fma_f32 v[144:145], v[24:25], s[12:13], v[54:55] op_sel_hi:[1,0,0]
	v_lshl_add_u64 v[24:25], v[16:17], 1, s[40:41]
	v_lshl_add_u64 v[28:29], v[20:21], 1, s[40:41]
	v_fmamk_f32 v32, v32, 0x3e0293ee, v54
	v_fmamk_f32 v34, v34, 0x3e0293ee, v54
	v_pk_fma_f32 v[150:151], v[30:31], s[12:13], v[54:55] op_sel_hi:[1,0,0]
	v_pk_fma_f32 v[158:159], v[26:27], s[12:13], v[54:55] op_sel_hi:[1,0,0]
	v_pk_fma_f32 v[146:147], v[22:23], s[12:13], v[54:55] op_sel_hi:[1,0,0]
	v_pk_fma_f32 v[154:155], v[18:19], s[12:13], v[54:55] op_sel_hi:[1,0,0]
	global_load_dwordx4 v[16:19], v[24:25], off offset:2560
	global_load_dwordx4 v[20:23], v[28:29], off offset:2560
	s_nop 0
	global_load_dwordx4 v[24:27], v[24:25], off offset:2048
	s_nop 0
	global_load_dwordx4 v[28:31], v[28:29], off offset:2048
	v_fmamk_f32 v33, v33, 0x3e0293ee, v54
	v_fmamk_f32 v35, v35, 0x3e0293ee, v54
	v_exp_f32_e32 v238, v32
	v_exp_f32_e32 v240, v34
	v_add_u32_e32 v32, 0x80, v50
	v_add_u32_e32 v34, 0xa0, v50
	v_exp_f32_e32 v239, v33
	v_exp_f32_e32 v246, v35
	v_mad_i64_i32 v[32:33], s[18:19], v32, s16, 0
	v_mad_i64_i32 v[34:35], s[18:19], v34, s16, 0
	v_or_b32_e32 v32, v32, v52
	v_or_b32_e32 v34, v34, v52
	v_lshl_add_u64 v[32:33], v[32:33], 1, s[40:41]
	v_lshl_add_u64 v[34:35], v[34:35], 1, s[40:41]
	global_load_dwordx4 v[128:131], v[32:33], off offset:2560
	global_load_dwordx4 v[132:135], v[34:35], off offset:2560
	global_load_dwordx4 v[136:139], v[32:33], off offset:2048
	global_load_dwordx4 v[140:143], v[34:35], off offset:2048
	v_mov_b32_e32 v53, v54
	s_waitcnt vmcnt(4)
	s_waitcnt vmcnt(7)
	ds_write_b128 v183, v[16:19] offset:16384
	s_waitcnt vmcnt(6)
	ds_write_b128 v184, v[20:23] offset:16384
	s_waitcnt vmcnt(5)
	ds_write_b128 v188, v[24:27] offset:49152
	s_waitcnt vmcnt(4)
	ds_write_b128 v189, v[28:31] offset:49152
	v_mad_i64_i32 v[16:17], s[18:19], v50, s20, 0
	v_mov_b32_e32 v18, 0x1800000
	v_fmamk_f32 v36, v36, 0x3e0293ee, v54
	v_fmamk_f32 v37, v37, 0x3e0293ee, v54
	v_fmamk_f32 v38, v38, 0x3e0293ee, v54
	v_fmamk_f32 v39, v39, 0x3e0293ee, v54
	v_fmamk_f32 v40, v40, 0x3e0293ee, v54
	v_fmamk_f32 v41, v41, 0x3e0293ee, v54
	v_fmamk_f32 v42, v42, 0x3e0293ee, v54
	v_fmamk_f32 v43, v43, 0x3e0293ee, v54
	v_fmamk_f32 v44, v44, 0x3e0293ee, v54
	v_fmamk_f32 v45, v45, 0x3e0293ee, v54
	v_fmamk_f32 v46, v46, 0x3e0293ee, v54
	v_fmac_f32_e32 v53, 0x3e0293ee, v47
	v_mad_i64_i32 v[16:17], s[18:19], s42, v18, v[16:17]
	v_and_b32_e32 v18, 15, v48
	v_exp_f32_e32 v247, v36
	v_exp_f32_e32 v248, v37
	v_exp_f32_e32 v249, v38
	v_exp_f32_e32 v250, v39
	v_exp_f32_e32 v251, v40
	v_exp_f32_e32 v252, v41
	v_exp_f32_e32 v253, v42
	v_exp_f32_e32 v241, v43
	v_exp_f32_e32 v243, v44
	v_exp_f32_e32 v244, v45
	v_exp_f32_e32 v245, v46
	v_exp_f32_e32 v193, v53
	v_lshlrev_b32_e32 v18, 4, v18
	s_addk_i32 s3, 0x4000
	v_or3_b32 v16, v16, s2, v18
	v_cmp_gt_u32_e64 s[40:41], 32, v49
	v_add_u32_e32 v187, s3, v51
	v_lshl_add_u64 v[178:179], s[44:45], 0, v[16:17]
	v_mov_b64_e32 v[62:63], v[14:15]
	v_mov_b64_e32 v[46:47], v[14:15]
	v_mov_b64_e32 v[30:31], v[14:15]
	v_mov_b64_e32 v[60:61], v[12:13]
	v_mov_b64_e32 v[58:59], v[10:11]
	v_mov_b64_e32 v[56:57], v[8:9]
	v_mov_b64_e32 v[54:55], v[6:7]
	v_mov_b64_e32 v[52:53], v[4:5]
	v_mov_b64_e32 v[50:51], v[2:3]
	v_mov_b64_e32 v[48:49], v[0:1]
	v_mov_b64_e32 v[44:45], v[12:13]
	v_mov_b64_e32 v[42:43], v[10:11]
	v_mov_b64_e32 v[40:41], v[8:9]
	v_mov_b64_e32 v[38:39], v[6:7]
	v_mov_b64_e32 v[36:37], v[4:5]
	v_mov_b64_e32 v[34:35], v[2:3]
	v_mov_b64_e32 v[32:33], v[0:1]
	v_mov_b64_e32 v[28:29], v[12:13]
	v_mov_b64_e32 v[26:27], v[10:11]
	v_mov_b64_e32 v[24:25], v[8:9]
	v_mov_b64_e32 v[22:23], v[6:7]
	v_mov_b64_e32 v[20:21], v[4:5]
	v_mov_b64_e32 v[18:19], v[2:3]
	v_mov_b64_e32 v[16:17], v[0:1]
	s_waitcnt lgkmcnt(0)
	s_barrier
	s_mov_b32 s90, 0
	s_movk_i32 s91, 0x4000
	s_mov_b32 s92, 0x10800
.LBB0_726:
	ds_read_b128 v[64:67], v190 offset:49152
	ds_read_b128 v[68:71], v190 offset:57344
	ds_read_b128 v[214:217], v205 offset:49152
	ds_read_b128 v[218:221], v205 offset:57344
	v_exp_f32_e32 v156, v156
	v_exp_f32_e32 v157, v157
	v_add_f32_e32 v209, v238, v239
	s_waitcnt lgkmcnt(3)
	v_mfma_f32_32x32x16_bf16 v[80:95], v[64:67], v[124:127], 0
	v_exp_f32_e32 v154, v154
	v_exp_f32_e32 v155, v155
	v_add_f32_e32 v209, v240, v209
	v_add_f32_e32 v209, v246, v209
	s_waitcnt lgkmcnt(2)
	v_mfma_f32_32x32x16_bf16 v[64:79], v[68:71], v[124:127], 0
	v_exp_f32_e32 v148, v148
	v_exp_f32_e32 v149, v149
	v_add_f32_e32 v209, v247, v209
	v_add_f32_e32 v209, v248, v209
	s_waitcnt lgkmcnt(1)
	v_mfma_f32_32x32x16_bf16 v[80:95], v[214:217], v[120:123], v[80:95]
	v_exp_f32_e32 v146, v146
	v_exp_f32_e32 v147, v147
	v_add_f32_e32 v209, v249, v209
	v_add_f32_e32 v209, v250, v209
	s_waitcnt lgkmcnt(0)
	v_mfma_f32_32x32x16_bf16 v[64:79], v[218:221], v[120:123], v[64:79]
	ds_read_b128 v[214:217], v204 offset:49152
	ds_read_b128 v[218:221], v204 offset:57344
	v_exp_f32_e32 v144, v144
	v_exp_f32_e32 v145, v145
	v_add_f32_e32 v209, v251, v209
	v_add_f32_e32 v209, v252, v209
	s_waitcnt lgkmcnt(1)
	v_mfma_f32_32x32x16_bf16 v[80:95], v[214:217], v[116:119], v[80:95]
	v_exp_f32_e32 v158, v158
	v_exp_f32_e32 v159, v159
	v_add_f32_e32 v209, v253, v209
	v_add_f32_e32 v209, v241, v209
	s_waitcnt lgkmcnt(0)
	v_mfma_f32_32x32x16_bf16 v[64:79], v[218:221], v[116:119], v[64:79]
	ds_read_b128 v[214:217], v202 offset:49152
	ds_read_b128 v[218:221], v202 offset:57344
	v_exp_f32_e32 v152, v152
	v_exp_f32_e32 v153, v153
	v_add_f32_e32 v209, v243, v209
	v_add_f32_e32 v209, v244, v209
	s_waitcnt lgkmcnt(1)
	v_mfma_f32_32x32x16_bf16 v[80:95], v[214:217], v[112:115], v[80:95]
	v_exp_f32_e32 v150, v150
	v_exp_f32_e32 v151, v151
	v_add_f32_e32 v209, v245, v209
	v_add_f32_e32 v209, v193, v209
	s_waitcnt lgkmcnt(0)
	v_mfma_f32_32x32x16_bf16 v[64:79], v[218:221], v[112:115], v[64:79]
	ds_read_b128 v[214:217], v191 offset:49152
	ds_read_b128 v[218:221], v191 offset:57344
	v_add_f32_e32 v209, v156, v209
	v_add_f32_e32 v209, v157, v209
	v_add_f32_e32 v209, v154, v209
	v_add_f32_e32 v209, v155, v209
	v_cvt_pk_bf16_f32 v160, v238, v239
	v_cvt_pk_bf16_f32 v162, v247, v248
	s_waitcnt lgkmcnt(1)
	v_mfma_f32_32x32x16_bf16 v[80:95], v[214:217], v[108:111], v[80:95]
	v_add_f32_e32 v209, v148, v209
	v_add_f32_e32 v209, v149, v209
	v_add_f32_e32 v209, v146, v209
	v_add_f32_e32 v209, v147, v209
	v_cvt_pk_bf16_f32 v161, v240, v246
	v_cvt_pk_bf16_f32 v163, v249, v250
	s_waitcnt lgkmcnt(0)
	v_mfma_f32_32x32x16_bf16 v[64:79], v[218:221], v[108:111], v[64:79]
	ds_read_b128 v[214:217], v203 offset:49152
	ds_read_b128 v[218:221], v203 offset:57344
	v_add_f32_e32 v209, v144, v209
	v_add_f32_e32 v209, v145, v209
	v_add_f32_e32 v209, v158, v209
	v_add_f32_e32 v209, v159, v209
	v_permlane32_swap_b32_e32 v160, v162
	v_permlane32_swap_b32_e32 v161, v163
	s_waitcnt lgkmcnt(1)
	v_mfma_f32_32x32x16_bf16 v[80:95], v[214:217], v[104:107], v[80:95]
	v_add_f32_e32 v209, v152, v209
	v_add_f32_e32 v209, v153, v209
	v_add_f32_e32 v209, v150, v209
	v_add_f32_e32 v209, v151, v209
	v_cvt_pk_bf16_f32 v170, v251, v252
	v_cvt_pk_bf16_f32 v172, v243, v244
	s_waitcnt lgkmcnt(0)
	v_mfma_f32_32x32x16_bf16 v[64:79], v[218:221], v[104:107], v[64:79]
	ds_read_b128 v[214:217], v206 offset:49152
	ds_read_b128 v[218:221], v206 offset:57344
	s_waitcnt vmcnt(0)
	v_add_u32_e32 v196, s92, v183
	v_add_u32_e32 v198, s92, v184
	ds_write_b128 v188, v[136:139] offset:32768
	ds_write_b128 v189, v[140:143] offset:32768
	ds_write_b128 v196, v[128:131]
	ds_write_b128 v198, v[132:135]
	v_mov_b32_e32 v210, v209
	v_cvt_pk_bf16_f32 v171, v253, v241
	v_cvt_pk_bf16_f32 v173, v245, v193
	v_cvt_pk_bf16_f32 v166, v156, v157
	v_cvt_pk_bf16_f32 v168, v148, v149
	s_waitcnt lgkmcnt(5)
	v_mfma_f32_32x32x16_bf16 v[80:95], v[214:217], v[100:103], v[80:95]
	v_permlane32_swap_b32_e32 v209, v210
	v_permlane32_swap_b32_e32 v170, v172
	v_permlane32_swap_b32_e32 v171, v173
	v_cvt_pk_bf16_f32 v167, v154, v155
	v_cvt_pk_bf16_f32 v169, v146, v147
	s_waitcnt lgkmcnt(4)
	v_mfma_f32_32x32x16_bf16 v[64:79], v[218:221], v[100:103], v[64:79]
	ds_read_b128 v[214:217], v207 offset:49152
	ds_read_b128 v[218:221], v207 offset:57344
	v_permlane32_swap_b32_e32 v166, v168
	v_cvt_pk_bf16_f32 v212, v144, v145
	v_cvt_pk_bf16_f32 v213, v158, v159
	s_waitcnt lgkmcnt(1)
	v_mfma_f32_32x32x16_bf16 v[80:95], v[214:217], v[96:99], v[80:95]
	v_permlane32_swap_b32_e32 v167, v169
	v_cvt_pk_bf16_f32 v214, v152, v153
	v_cvt_pk_bf16_f32 v215, v150, v151
	s_waitcnt lgkmcnt(0)
	v_mfma_f32_32x32x16_bf16 v[64:79], v[218:221], v[96:99], v[64:79]
	v_permlane32_swap_b32_e32 v212, v214
	v_permlane32_swap_b32_e32 v213, v215
	v_add_u32_e32 v187, s90, v182
	s_mov_b32 s2, 0xfffb8000
	v_add_co_u32_e32 v148, vcc, s2, v178
	s_mov_b32 s2, 0xfffd0000
	s_nop 0
	v_addc_co_u32_e32 v149, vcc, -1, v179, vcc
	v_add_co_u32_e32 v152, vcc, s2, v178
	s_nop 1
	v_addc_co_u32_e32 v153, vcc, -1, v179, vcc
	global_load_dwordx4 v[144:147], v[148:149], off
	s_nop 0
	global_load_dwordx4 v[148:151], v[148:149], off offset:-512
	s_nop 0
	global_load_dwordx4 v[156:159], v[152:153], off
	s_nop 0
	global_load_dwordx4 v[152:155], v[152:153], off offset:-512
	ds_read_b64_tr_b16 v[216:217], v187 offset:0
	ds_read_b64_tr_b16 v[218:219], v187 offset:0x800
	ds_read_b64_tr_b16 v[220:221], v187 offset:0x1000
	ds_read_b64_tr_b16 v[222:223], v187 offset:0x1800
	ds_read_b64_tr_b16 v[224:225], v187 offset:0x2000
	ds_read_b64_tr_b16 v[226:227], v187 offset:0x2800
	ds_read_b64_tr_b16 v[228:229], v187 offset:0x3000
	ds_read_b64_tr_b16 v[230:231], v187 offset:0x3800
	v_max_f32_e32 v196, v81, v81
	v_max_f32_e32 v197, v80, v80
	v_max_f32_e32 v196, v197, v196
	v_max3_f32 v196, v196, v82, v83
	v_max3_f32 v196, v196, v84, v85
	v_max3_f32 v196, v196, v86, v87
	v_max3_f32 v196, v196, v88, v89
	s_waitcnt lgkmcnt(0)
	s_nop 0
	v_mfma_f32_32x32x16_bf16 v[0:15], v[160:163], v[216:219], v[0:15]
	ds_read_b64_tr_b16 v[216:217], v187 offset:0x200
	ds_read_b64_tr_b16 v[218:219], v187 offset:0xa00
	v_max3_f32 v196, v196, v90, v91
	v_max3_f32 v196, v196, v92, v93
	v_max3_f32 v196, v196, v94, v95
	v_max3_f32 v196, v196, v64, v65
	v_mfma_f32_32x32x16_bf16 v[0:15], v[170:173], v[220:223], v[0:15]
	ds_read_b64_tr_b16 v[220:221], v187 offset:0x1200
	ds_read_b64_tr_b16 v[222:223], v187 offset:0x1a00
	v_max3_f32 v196, v196, v66, v67
	v_max3_f32 v196, v196, v68, v69
	v_max3_f32 v196, v196, v70, v71
	v_max3_f32 v196, v196, v72, v73
	v_mfma_f32_32x32x16_bf16 v[0:15], v[166:169], v[224:227], v[0:15]
	ds_read_b64_tr_b16 v[224:225], v187 offset:0x2200
	ds_read_b64_tr_b16 v[226:227], v187 offset:0x2a00
	v_max3_f32 v196, v196, v74, v75
	v_max3_f32 v196, v196, v76, v77
	v_max3_f32 v196, v196, v78, v79
	v_mov_b32_e32 v197, v196
	v_mfma_f32_32x32x16_bf16 v[0:15], v[212:215], v[228:231], v[0:15]
	ds_read_b64_tr_b16 v[228:229], v187 offset:0x3200
	ds_read_b64_tr_b16 v[230:231], v187 offset:0x3a00
	v_permlane32_swap_b32_e32 v196, v197
	v_max_f32_e32 v197, v197, v197
	v_max_f32_e32 v196, v196, v196
	v_max_f32_e32 v196, v196, v197
	s_waitcnt lgkmcnt(0)
	v_mfma_f32_32x32x16_bf16 v[48:63], v[160:163], v[216:219], v[48:63]
	ds_read_b64_tr_b16 v[216:217], v187 offset:0x400
	ds_read_b64_tr_b16 v[218:219], v187 offset:0xc00
	v_sub_f32_e32 v197, v196, v164
	v_cmp_ge_f32_e32 vcc, s85, v197
	v_max_f32_e32 v197, v164, v164
	v_max_f32_e32 v196, v197, v196
	v_sub_f32_e32 v197, v164, v196
	v_mul_f32_e32 v197, 0x3e0293ee, v197
	v_mfma_f32_32x32x16_bf16 v[48:63], v[170:173], v[220:223], v[48:63]
	ds_read_b64_tr_b16 v[220:221], v187 offset:0x1400
	ds_read_b64_tr_b16 v[222:223], v187 offset:0x1c00
	v_exp_f32_e32 v197, v197
	s_cmp_eq_u64 vcc, exec
	s_cselect_b64 s[42:43], -1, 0
	v_mfma_f32_32x32x16_bf16 v[48:63], v[166:169], v[224:227], v[48:63]
	ds_read_b64_tr_b16 v[224:225], v187 offset:0x2400
	ds_read_b64_tr_b16 v[226:227], v187 offset:0x2c00
	v_cndmask_b32_e64 v211, v196, v164, s[42:43]
	v_mul_f32_e32 v198, 0xbe0293ee, v211
	v_fmamk_f32 v80, v80, 0x3e0293ee, v198
	v_fmamk_f32 v81, v81, 0x3e0293ee, v198
	v_fmamk_f32 v82, v82, 0x3e0293ee, v198
	v_fmamk_f32 v83, v83, 0x3e0293ee, v198
	v_mfma_f32_32x32x16_bf16 v[48:63], v[212:215], v[228:231], v[48:63]
	ds_read_b64_tr_b16 v[228:229], v187 offset:0x3400
	ds_read_b64_tr_b16 v[230:231], v187 offset:0x3c00
	v_fmamk_f32 v84, v84, 0x3e0293ee, v198
	v_fmamk_f32 v85, v85, 0x3e0293ee, v198
	v_fmamk_f32 v86, v86, 0x3e0293ee, v198
	v_fmamk_f32 v87, v87, 0x3e0293ee, v198
	v_exp_f32_e32 v238, v80
	v_exp_f32_e32 v239, v81
	s_waitcnt lgkmcnt(0)
	v_mfma_f32_32x32x16_bf16 v[32:47], v[160:163], v[216:219], v[32:47]
	ds_read_b64_tr_b16 v[216:217], v187 offset:0x600
	ds_read_b64_tr_b16 v[218:219], v187 offset:0xe00
	v_fmamk_f32 v88, v88, 0x3e0293ee, v198
	v_fmamk_f32 v89, v89, 0x3e0293ee, v198
	v_fmamk_f32 v90, v90, 0x3e0293ee, v198
	v_fmamk_f32 v91, v91, 0x3e0293ee, v198
	v_exp_f32_e32 v240, v82
	v_exp_f32_e32 v246, v83
	v_mfma_f32_32x32x16_bf16 v[32:47], v[170:173], v[220:223], v[32:47]
	ds_read_b64_tr_b16 v[220:221], v187 offset:0x1600
	ds_read_b64_tr_b16 v[222:223], v187 offset:0x1e00
	v_fmamk_f32 v92, v92, 0x3e0293ee, v198
	v_fmamk_f32 v93, v93, 0x3e0293ee, v198
	v_fmamk_f32 v94, v94, 0x3e0293ee, v198
	v_fmamk_f32 v95, v95, 0x3e0293ee, v198
	v_exp_f32_e32 v247, v84
	v_exp_f32_e32 v248, v85
	v_mfma_f32_32x32x16_bf16 v[32:47], v[166:169], v[224:227], v[32:47]
	ds_read_b64_tr_b16 v[224:225], v187 offset:0x2600
	ds_read_b64_tr_b16 v[226:227], v187 offset:0x2e00
	v_exp_f32_e32 v249, v86
	v_exp_f32_e32 v250, v87
	v_exp_f32_e32 v251, v88
	v_mfma_f32_32x32x16_bf16 v[32:47], v[212:215], v[228:231], v[32:47]
	ds_read_b64_tr_b16 v[228:229], v187 offset:0x3600
	ds_read_b64_tr_b16 v[230:231], v187 offset:0x3e00
	v_exp_f32_e32 v252, v89
	v_exp_f32_e32 v253, v90
	v_exp_f32_e32 v241, v91
	s_waitcnt lgkmcnt(0)
	v_mfma_f32_32x32x16_bf16 v[16:31], v[160:163], v[216:219], v[16:31]
	v_exp_f32_e32 v243, v92
	v_exp_f32_e32 v244, v93
	v_mfma_f32_32x32x16_bf16 v[16:31], v[170:173], v[220:223], v[16:31]
	v_exp_f32_e32 v245, v94
	v_exp_f32_e32 v193, v95
	v_mfma_f32_32x32x16_bf16 v[16:31], v[166:169], v[224:227], v[16:31]
	v_mfma_f32_32x32x16_bf16 v[16:31], v[212:215], v[228:231], v[16:31]
	v_cndmask_b32_e64 v213, v197, 1.0, s[42:43]
	v_cmp_gt_f32_e32 vcc, 1.0, v213
	v_mul_f32_e32 v212, 0xbe0293ee, v211
	s_add_i32 s11, s11, 2
	s_nop 3
	s_cbranch_vccz .LBB0_730
	s_and_saveexec_b64 s[2:3], s[40:41]
	ds_write_b32 v185, v213 offset:128
	s_or_b64 exec, exec, s[2:3]
	s_waitcnt lgkmcnt(0)
	v_add_u32_e32 v161, v177, v194
	ds_read_b128 v[166:169], v161 offset:224
	ds_read_b128 v[170:173], v161 offset:192
	ds_read_b128 v[214:217], v161 offset:160
	ds_read_b128 v[218:221], v161 offset:128
	s_waitcnt lgkmcnt(3)
	v_pk_mul_f32 v[12:13], v[12:13], v[166:167]
	s_waitcnt lgkmcnt(2)
	v_pk_mul_f32 v[8:9], v[8:9], v[170:171]
	s_waitcnt lgkmcnt(1)
	v_pk_mul_f32 v[4:5], v[4:5], v[214:215]
	v_pk_mul_f32 v[14:15], v[14:15], v[168:169]
	v_pk_mul_f32 v[10:11], v[10:11], v[172:173]
	v_pk_mul_f32 v[6:7], v[6:7], v[216:217]
	s_waitcnt lgkmcnt(0)
	v_pk_mul_f32 v[2:3], v[2:3], v[220:221]
	v_pk_mul_f32 v[0:1], v[0:1], v[218:219]
	v_pk_mul_f32 v[60:61], v[60:61], v[166:167]
	v_pk_mul_f32 v[56:57], v[56:57], v[170:171]
	v_pk_mul_f32 v[52:53], v[52:53], v[214:215]
	v_pk_mul_f32 v[62:63], v[62:63], v[168:169]
	v_pk_mul_f32 v[58:59], v[58:59], v[172:173]
	v_pk_mul_f32 v[54:55], v[54:55], v[216:217]
	v_pk_mul_f32 v[50:51], v[50:51], v[220:221]
	v_pk_mul_f32 v[48:49], v[48:49], v[218:219]
	v_pk_mul_f32 v[44:45], v[44:45], v[166:167]
	v_pk_mul_f32 v[40:41], v[40:41], v[170:171]
	v_pk_mul_f32 v[36:37], v[36:37], v[214:215]
	v_pk_mul_f32 v[46:47], v[46:47], v[168:169]
	v_pk_mul_f32 v[42:43], v[42:43], v[172:173]
	v_pk_mul_f32 v[38:39], v[38:39], v[216:217]
	v_pk_mul_f32 v[34:35], v[34:35], v[220:221]
	v_pk_mul_f32 v[32:33], v[32:33], v[218:219]
	v_pk_mul_f32 v[28:29], v[28:29], v[166:167]
	v_pk_mul_f32 v[24:25], v[24:25], v[170:171]
	v_pk_mul_f32 v[20:21], v[20:21], v[214:215]
	v_pk_mul_f32 v[30:31], v[30:31], v[168:169]
	v_pk_mul_f32 v[26:27], v[26:27], v[172:173]
	v_pk_mul_f32 v[22:23], v[22:23], v[216:217]
	v_pk_mul_f32 v[18:19], v[18:19], v[220:221]
	v_pk_mul_f32 v[16:17], v[16:17], v[218:219]
.LBB0_730:
	v_fmamk_f32 v215, v69, 0x3e0293ee, v212
	v_fmamk_f32 v214, v76, 0x3e0293ee, v212
	v_fmamk_f32 v222, v64, 0x3e0293ee, v212
	v_fmamk_f32 v223, v65, 0x3e0293ee, v212
	v_fmamk_f32 v224, v66, 0x3e0293ee, v212
	v_fmamk_f32 v225, v67, 0x3e0293ee, v212
	v_fmamk_f32 v226, v68, 0x3e0293ee, v212
	v_fmamk_f32 v216, v70, 0x3e0293ee, v212
	v_fmamk_f32 v217, v71, 0x3e0293ee, v212
	v_fmamk_f32 v218, v72, 0x3e0293ee, v212
	v_fmamk_f32 v219, v73, 0x3e0293ee, v212
	v_fmamk_f32 v220, v74, 0x3e0293ee, v212
	v_fmamk_f32 v221, v75, 0x3e0293ee, v212
	v_fmamk_f32 v227, v77, 0x3e0293ee, v212
	v_fmamk_f32 v228, v78, 0x3e0293ee, v212
	v_fmac_f32_e32 v212, 0x3e0293ee, v79
	s_waitcnt lgkmcnt(0)
	s_barrier
	ds_read_b128 v[64:67], v190 offset:32768
	ds_read_b128 v[68:71], v190 offset:40960
	ds_read_b128 v[230:233], v205 offset:32768
	ds_read_b128 v[234:237], v205 offset:40960
	v_exp_f32_e32 v222, v222
	v_exp_f32_e32 v223, v223
	v_add_f32_e32 v196, v238, v239
	s_waitcnt lgkmcnt(3)
	v_mfma_f32_32x32x16_bf16 v[80:95], v[64:67], v[124:127], 0
	v_exp_f32_e32 v224, v224
	v_exp_f32_e32 v225, v225
	v_add_f32_e32 v196, v240, v196
	v_add_f32_e32 v196, v246, v196
	s_waitcnt lgkmcnt(2)
	v_mfma_f32_32x32x16_bf16 v[64:79], v[68:71], v[124:127], 0
	v_exp_f32_e32 v226, v226
	v_exp_f32_e32 v215, v215
	v_add_f32_e32 v196, v247, v196
	v_add_f32_e32 v196, v248, v196
	s_waitcnt lgkmcnt(1)
	v_mfma_f32_32x32x16_bf16 v[80:95], v[230:233], v[120:123], v[80:95]
	v_exp_f32_e32 v216, v216
	v_exp_f32_e32 v217, v217
	v_add_f32_e32 v196, v249, v196
	v_add_f32_e32 v196, v250, v196
	s_waitcnt lgkmcnt(0)
	v_mfma_f32_32x32x16_bf16 v[64:79], v[234:237], v[120:123], v[64:79]
	ds_read_b128 v[230:233], v204 offset:32768
	ds_read_b128 v[234:237], v204 offset:40960
	v_exp_f32_e32 v218, v218
	v_exp_f32_e32 v219, v219
	v_add_f32_e32 v196, v251, v196
	v_add_f32_e32 v196, v252, v196
	s_waitcnt lgkmcnt(1)
	v_mfma_f32_32x32x16_bf16 v[80:95], v[230:233], v[116:119], v[80:95]
	v_exp_f32_e32 v220, v220
	v_exp_f32_e32 v221, v221
	v_add_f32_e32 v196, v253, v196
	v_add_f32_e32 v196, v241, v196
	s_waitcnt lgkmcnt(0)
	v_mfma_f32_32x32x16_bf16 v[64:79], v[234:237], v[116:119], v[64:79]
	ds_read_b128 v[230:233], v202 offset:32768
	ds_read_b128 v[234:237], v202 offset:40960
	v_exp_f32_e32 v214, v214
	v_exp_f32_e32 v227, v227
	v_add_f32_e32 v196, v243, v196
	v_add_f32_e32 v196, v244, v196
	s_waitcnt lgkmcnt(1)
	v_mfma_f32_32x32x16_bf16 v[80:95], v[230:233], v[112:115], v[80:95]
	v_exp_f32_e32 v228, v228
	v_exp_f32_e32 v212, v212
	v_add_f32_e32 v196, v245, v196
	v_add_f32_e32 v196, v193, v196
	s_waitcnt lgkmcnt(0)
	v_mfma_f32_32x32x16_bf16 v[64:79], v[234:237], v[112:115], v[64:79]
	ds_read_b128 v[230:233], v191 offset:32768
	ds_read_b128 v[234:237], v191 offset:40960
	v_add_f32_e32 v196, v222, v196
	v_add_f32_e32 v196, v223, v196
	v_add_f32_e32 v196, v224, v196
	v_add_f32_e32 v196, v225, v196
	v_cvt_pk_bf16_f32 v160, v238, v239
	v_cvt_pk_bf16_f32 v162, v247, v248
	s_waitcnt lgkmcnt(1)
	v_mfma_f32_32x32x16_bf16 v[80:95], v[230:233], v[108:111], v[80:95]
	v_add_f32_e32 v196, v226, v196
	v_add_f32_e32 v196, v215, v196
	v_add_f32_e32 v196, v216, v196
	v_add_f32_e32 v196, v217, v196
	v_cvt_pk_bf16_f32 v161, v240, v246
	v_cvt_pk_bf16_f32 v163, v249, v250
	s_waitcnt lgkmcnt(0)
	v_mfma_f32_32x32x16_bf16 v[64:79], v[234:237], v[108:111], v[64:79]
	ds_read_b128 v[230:233], v203 offset:32768
	ds_read_b128 v[234:237], v203 offset:40960
	v_add_f32_e32 v196, v218, v196
	v_add_f32_e32 v196, v219, v196
	v_add_f32_e32 v196, v220, v196
	v_add_f32_e32 v196, v221, v196
	v_permlane32_swap_b32_e32 v160, v162
	v_permlane32_swap_b32_e32 v161, v163
	s_waitcnt lgkmcnt(1)
	v_mfma_f32_32x32x16_bf16 v[80:95], v[230:233], v[104:107], v[80:95]
	v_add_f32_e32 v196, v214, v196
	v_add_f32_e32 v196, v227, v196
	v_add_f32_e32 v196, v228, v196
	v_add_f32_e32 v196, v212, v196
	v_cvt_pk_bf16_f32 v164, v251, v252
	v_cvt_pk_bf16_f32 v166, v243, v244
	s_waitcnt lgkmcnt(0)
	v_mfma_f32_32x32x16_bf16 v[64:79], v[234:237], v[104:107], v[64:79]
	ds_read_b128 v[230:233], v206 offset:32768
	ds_read_b128 v[234:237], v206 offset:40960
	s_waitcnt vmcnt(0)
	ds_write_b128 v188, v[148:151] offset:49152
	ds_write_b128 v189, v[152:155] offset:49152
	v_add_u32_e32 v197, s90, v183
	ds_write_b128 v197, v[144:147]
	v_add_u32_e32 v197, s90, v184
	ds_write_b128 v197, v[156:159]
	v_mov_b32_e32 v198, v196
	v_cvt_pk_bf16_f32 v165, v253, v241
	v_cvt_pk_bf16_f32 v167, v245, v193
	v_cvt_pk_bf16_f32 v168, v222, v223
	v_cvt_pk_bf16_f32 v170, v226, v215
	s_waitcnt lgkmcnt(5)
	v_mfma_f32_32x32x16_bf16 v[80:95], v[230:233], v[100:103], v[80:95]
	v_permlane32_swap_b32_e32 v196, v198
	v_permlane32_swap_b32_e32 v164, v166
	v_permlane32_swap_b32_e32 v165, v167
	v_cvt_pk_bf16_f32 v169, v224, v225
	v_cvt_pk_bf16_f32 v171, v216, v217
	s_waitcnt lgkmcnt(4)
	v_mfma_f32_32x32x16_bf16 v[64:79], v[234:237], v[100:103], v[64:79]
	ds_read_b128 v[230:233], v207 offset:32768
	ds_read_b128 v[234:237], v207 offset:40960
	v_permlane32_swap_b32_e32 v168, v170
	v_cvt_pk_bf16_f32 v172, v218, v219
	v_cvt_pk_bf16_f32 v173, v220, v221
	s_waitcnt lgkmcnt(1)
	v_mfma_f32_32x32x16_bf16 v[80:95], v[230:233], v[96:99], v[80:95]
	v_permlane32_swap_b32_e32 v169, v171
	v_cvt_pk_bf16_f32 v174, v214, v227
	v_cvt_pk_bf16_f32 v175, v228, v212
	s_waitcnt lgkmcnt(0)
	v_mfma_f32_32x32x16_bf16 v[64:79], v[234:237], v[96:99], v[64:79]
	v_permlane32_swap_b32_e32 v172, v174
	v_permlane32_swap_b32_e32 v173, v175
	v_add_f32_e32 v209, v209, v210
	v_fmac_f32_e32 v209, v208, v186
	v_add_f32_e32 v186, v196, v198
	v_fmac_f32_e32 v186, v209, v213
	v_add_u32_e32 v187, s91, v182
	s_cmpk_gt_u32 s11, 0x7c
	s_cselect_b64 s[20:21], -1, 0
	s_and_b64 vcc, exec, s[20:21]
	s_cbranch_vccnz .LBB0_732
	v_add_co_u32_e32 v132, vcc, 0xfffe8000, v178
	s_nop 1
	v_addc_co_u32_e32 v133, vcc, -1, v179, vcc
	global_load_dwordx4 v[128:131], v[132:133], off
	global_load_dwordx4 v[136:139], v[132:133], off offset:-512
	s_nop 0
	global_load_dwordx4 v[132:135], v[178:179], off
	global_load_dwordx4 v[140:143], v[178:179], off offset:-512
.LBB0_732:
	ds_read_b64_tr_b16 v[216:217], v187 offset:0
	ds_read_b64_tr_b16 v[218:219], v187 offset:0x800
	ds_read_b64_tr_b16 v[220:221], v187 offset:0x1000
	ds_read_b64_tr_b16 v[222:223], v187 offset:0x1800
	ds_read_b64_tr_b16 v[224:225], v187 offset:0x2000
	ds_read_b64_tr_b16 v[226:227], v187 offset:0x2800
	ds_read_b64_tr_b16 v[228:229], v187 offset:0x3000
	ds_read_b64_tr_b16 v[230:231], v187 offset:0x3800
	v_max_f32_e32 v196, v81, v81
	v_max_f32_e32 v197, v80, v80
	v_max_f32_e32 v196, v197, v196
	v_max3_f32 v196, v196, v82, v83
	v_max3_f32 v196, v196, v84, v85
	v_max3_f32 v196, v196, v86, v87
	v_max3_f32 v196, v196, v88, v89
	s_waitcnt lgkmcnt(0)
	s_nop 0
	v_mfma_f32_32x32x16_bf16 v[0:15], v[160:163], v[216:219], v[0:15]
	ds_read_b64_tr_b16 v[216:217], v187 offset:0x200
	ds_read_b64_tr_b16 v[218:219], v187 offset:0xa00
	v_max3_f32 v196, v196, v90, v91
	v_max3_f32 v196, v196, v92, v93
	v_max3_f32 v196, v196, v94, v95
	v_max3_f32 v196, v196, v64, v65
	v_mfma_f32_32x32x16_bf16 v[0:15], v[164:167], v[220:223], v[0:15]
	ds_read_b64_tr_b16 v[220:221], v187 offset:0x1200
	ds_read_b64_tr_b16 v[222:223], v187 offset:0x1a00
	v_max3_f32 v196, v196, v66, v67
	v_max3_f32 v196, v196, v68, v69
	v_max3_f32 v196, v196, v70, v71
	v_max3_f32 v196, v196, v72, v73
	v_mfma_f32_32x32x16_bf16 v[0:15], v[168:171], v[224:227], v[0:15]
	ds_read_b64_tr_b16 v[224:225], v187 offset:0x2200
	ds_read_b64_tr_b16 v[226:227], v187 offset:0x2a00
	v_max3_f32 v196, v196, v74, v75
	v_max3_f32 v196, v196, v76, v77
	v_max3_f32 v196, v196, v78, v79
	v_mov_b32_e32 v197, v196
	v_mfma_f32_32x32x16_bf16 v[0:15], v[172:175], v[228:231], v[0:15]
	ds_read_b64_tr_b16 v[228:229], v187 offset:0x3200
	ds_read_b64_tr_b16 v[230:231], v187 offset:0x3a00
	v_permlane32_swap_b32_e32 v196, v197
	v_max_f32_e32 v197, v197, v197
	v_max_f32_e32 v196, v196, v196
	v_max_f32_e32 v196, v196, v197
	s_waitcnt lgkmcnt(0)
	v_mfma_f32_32x32x16_bf16 v[48:63], v[160:163], v[216:219], v[48:63]
	ds_read_b64_tr_b16 v[216:217], v187 offset:0x400
	ds_read_b64_tr_b16 v[218:219], v187 offset:0xc00
	v_sub_f32_e32 v197, v196, v211
	v_cmp_ge_f32_e32 vcc, s85, v197
	v_max_f32_e32 v197, v211, v211
	v_max_f32_e32 v197, v197, v196
	v_sub_f32_e32 v196, v211, v197
	v_mul_f32_e32 v196, 0x3e0293ee, v196
	v_mfma_f32_32x32x16_bf16 v[48:63], v[164:167], v[220:223], v[48:63]
	ds_read_b64_tr_b16 v[220:221], v187 offset:0x1400
	ds_read_b64_tr_b16 v[222:223], v187 offset:0x1c00
	v_exp_f32_e32 v196, v196
	s_cmp_eq_u64 vcc, exec
	s_cselect_b64 s[42:43], -1, 0
	v_mfma_f32_32x32x16_bf16 v[48:63], v[168:171], v[224:227], v[48:63]
	ds_read_b64_tr_b16 v[224:225], v187 offset:0x2400
	ds_read_b64_tr_b16 v[226:227], v187 offset:0x2c00
	v_cndmask_b32_e64 v197, v197, v211, s[42:43]
	v_mul_f32_e32 v198, 0xbe0293ee, v197
	v_fmamk_f32 v80, v80, 0x3e0293ee, v198
	v_fmamk_f32 v81, v81, 0x3e0293ee, v198
	v_fmamk_f32 v82, v82, 0x3e0293ee, v198
	v_fmamk_f32 v83, v83, 0x3e0293ee, v198
	v_mfma_f32_32x32x16_bf16 v[48:63], v[172:175], v[228:231], v[48:63]
	ds_read_b64_tr_b16 v[228:229], v187 offset:0x3400
	ds_read_b64_tr_b16 v[230:231], v187 offset:0x3c00
	v_fmamk_f32 v84, v84, 0x3e0293ee, v198
	v_fmamk_f32 v85, v85, 0x3e0293ee, v198
	v_fmamk_f32 v86, v86, 0x3e0293ee, v198
	v_fmamk_f32 v87, v87, 0x3e0293ee, v198
	v_exp_f32_e32 v238, v80
	v_exp_f32_e32 v239, v81
	s_waitcnt lgkmcnt(0)
	v_mfma_f32_32x32x16_bf16 v[32:47], v[160:163], v[216:219], v[32:47]
	ds_read_b64_tr_b16 v[216:217], v187 offset:0x600
	ds_read_b64_tr_b16 v[218:219], v187 offset:0xe00
	v_fmamk_f32 v88, v88, 0x3e0293ee, v198
	v_fmamk_f32 v89, v89, 0x3e0293ee, v198
	v_fmamk_f32 v90, v90, 0x3e0293ee, v198
	v_fmamk_f32 v91, v91, 0x3e0293ee, v198
	v_exp_f32_e32 v240, v82
	v_exp_f32_e32 v246, v83
	v_mfma_f32_32x32x16_bf16 v[32:47], v[164:167], v[220:223], v[32:47]
	ds_read_b64_tr_b16 v[220:221], v187 offset:0x1600
	ds_read_b64_tr_b16 v[222:223], v187 offset:0x1e00
	v_fmamk_f32 v92, v92, 0x3e0293ee, v198
	v_fmamk_f32 v93, v93, 0x3e0293ee, v198
	v_fmamk_f32 v94, v94, 0x3e0293ee, v198
	v_fmamk_f32 v95, v95, 0x3e0293ee, v198
	v_exp_f32_e32 v247, v84
	v_exp_f32_e32 v248, v85
	v_mfma_f32_32x32x16_bf16 v[32:47], v[168:171], v[224:227], v[32:47]
	ds_read_b64_tr_b16 v[224:225], v187 offset:0x2600
	ds_read_b64_tr_b16 v[226:227], v187 offset:0x2e00
	v_exp_f32_e32 v249, v86
	v_exp_f32_e32 v250, v87
	v_exp_f32_e32 v251, v88
	v_mfma_f32_32x32x16_bf16 v[32:47], v[172:175], v[228:231], v[32:47]
	ds_read_b64_tr_b16 v[228:229], v187 offset:0x3600
	ds_read_b64_tr_b16 v[230:231], v187 offset:0x3e00
	v_exp_f32_e32 v252, v89
	v_exp_f32_e32 v253, v90
	v_exp_f32_e32 v241, v91
	s_waitcnt lgkmcnt(0)
	v_mfma_f32_32x32x16_bf16 v[16:31], v[160:163], v[216:219], v[16:31]
	v_exp_f32_e32 v243, v92
	v_exp_f32_e32 v244, v93
	v_mfma_f32_32x32x16_bf16 v[16:31], v[164:167], v[220:223], v[16:31]
	v_exp_f32_e32 v245, v94
	v_exp_f32_e32 v193, v95
	v_mfma_f32_32x32x16_bf16 v[16:31], v[168:171], v[224:227], v[16:31]
	v_mfma_f32_32x32x16_bf16 v[16:31], v[172:175], v[228:231], v[16:31]
	v_cndmask_b32_e64 v160, v196, 1.0, s[42:43]
	v_cmp_gt_f32_e32 vcc, 1.0, v160
	v_mov_b32_e32 v164, v197
	s_mov_b32 s98, s92
	s_mov_b32 s92, s91
	s_mov_b32 s91, s90
	s_mov_b32 s90, s98
	s_nop 0
	s_cbranch_vccz .LBB0_736
	s_and_saveexec_b64 s[2:3], s[40:41]
	ds_write_b32 v185, v160 offset:128
	s_or_b64 exec, exec, s[2:3]
	s_waitcnt lgkmcnt(0)
	v_add_u32_e32 v156, v177, v194
	ds_read_b128 v[144:147], v156 offset:224
	ds_read_b128 v[148:151], v156 offset:192
	ds_read_b128 v[152:155], v156 offset:160
	ds_read_b128 v[156:159], v156 offset:128
	s_waitcnt lgkmcnt(3)
	v_pk_mul_f32 v[12:13], v[12:13], v[144:145]
	s_waitcnt lgkmcnt(2)
	v_pk_mul_f32 v[8:9], v[8:9], v[148:149]
	s_waitcnt lgkmcnt(1)
	v_pk_mul_f32 v[4:5], v[4:5], v[152:153]
	v_pk_mul_f32 v[14:15], v[14:15], v[146:147]
	v_pk_mul_f32 v[10:11], v[10:11], v[150:151]
	v_pk_mul_f32 v[6:7], v[6:7], v[154:155]
	s_waitcnt lgkmcnt(0)
	v_pk_mul_f32 v[2:3], v[2:3], v[158:159]
	v_pk_mul_f32 v[0:1], v[0:1], v[156:157]
	v_pk_mul_f32 v[60:61], v[60:61], v[144:145]
	v_pk_mul_f32 v[56:57], v[56:57], v[148:149]
	v_pk_mul_f32 v[52:53], v[52:53], v[152:153]
	v_pk_mul_f32 v[62:63], v[62:63], v[146:147]
	v_pk_mul_f32 v[58:59], v[58:59], v[150:151]
	v_pk_mul_f32 v[54:55], v[54:55], v[154:155]
	v_pk_mul_f32 v[50:51], v[50:51], v[158:159]
	v_pk_mul_f32 v[48:49], v[48:49], v[156:157]
	v_pk_mul_f32 v[44:45], v[44:45], v[144:145]
	v_pk_mul_f32 v[40:41], v[40:41], v[148:149]
	v_pk_mul_f32 v[36:37], v[36:37], v[152:153]
	v_pk_mul_f32 v[46:47], v[46:47], v[146:147]
	v_pk_mul_f32 v[42:43], v[42:43], v[150:151]
	v_pk_mul_f32 v[38:39], v[38:39], v[154:155]
	v_pk_mul_f32 v[34:35], v[34:35], v[158:159]
	v_pk_mul_f32 v[32:33], v[32:33], v[156:157]
	v_pk_mul_f32 v[28:29], v[28:29], v[144:145]
	v_pk_mul_f32 v[24:25], v[24:25], v[148:149]
	v_pk_mul_f32 v[20:21], v[20:21], v[152:153]
	v_pk_mul_f32 v[30:31], v[30:31], v[146:147]
	v_pk_mul_f32 v[26:27], v[26:27], v[150:151]
	v_pk_mul_f32 v[22:23], v[22:23], v[154:155]
	v_pk_mul_f32 v[18:19], v[18:19], v[158:159]
	v_pk_mul_f32 v[16:17], v[16:17], v[156:157]
.LBB0_736:
	v_mul_f32_e32 v150, 0xbe0293ee, v164
	v_mov_b32_e32 v151, v150
	v_pk_fma_f32 v[156:157], v[64:65], s[12:13], v[150:151] op_sel_hi:[1,0,0]
	v_pk_fma_f32 v[154:155], v[66:67], s[12:13], v[150:151] op_sel_hi:[1,0,0]
	v_pk_fma_f32 v[148:149], v[68:69], s[12:13], v[150:151] op_sel_hi:[1,0,0]
	v_pk_fma_f32 v[146:147], v[70:71], s[12:13], v[150:151] op_sel_hi:[1,0,0]
	v_pk_fma_f32 v[144:145], v[72:73], s[12:13], v[150:151] op_sel_hi:[1,0,0]
	v_pk_fma_f32 v[158:159], v[74:75], s[12:13], v[150:151] op_sel_hi:[1,0,0]
	v_pk_fma_f32 v[152:153], v[76:77], s[12:13], v[150:151] op_sel_hi:[1,0,0]
	v_pk_fma_f32 v[150:151], v[78:79], s[12:13], v[150:151] op_sel_hi:[1,0,0]
	s_mov_b64 s[2:3], 0x60000
	v_lshl_add_u64 v[178:179], v[178:179], 0, s[2:3]
	s_and_b64 vcc, exec, s[20:21]
	s_waitcnt lgkmcnt(0)
	s_barrier
	s_cbranch_vccnz .LBB0_738
	v_mov_b32_e32 v208, v160
	s_branch .LBB0_726
.LBB0_738:
	v_add_u32_e32 v187, 0x4000, v182
	ds_read_b128 v[64:67], v190 offset:49152
	ds_read_b128 v[68:71], v190 offset:57344
	s_waitcnt lgkmcnt(1)
	v_mfma_f32_32x32x16_bf16 v[80:95], v[64:67], v[124:127], 0
	s_waitcnt lgkmcnt(0)
	v_mfma_f32_32x32x16_bf16 v[64:79], v[68:71], v[124:127], 0
	ds_read_b128 v[124:127], v205 offset:49152
	ds_read_b128 v[128:131], v205 offset:57344
	s_waitcnt lgkmcnt(1)
	v_mfma_f32_32x32x16_bf16 v[80:95], v[124:127], v[120:123], v[80:95]
	s_waitcnt lgkmcnt(0)
	v_mfma_f32_32x32x16_bf16 v[64:79], v[128:131], v[120:123], v[64:79]
	ds_read_b128 v[120:123], v204 offset:49152
	ds_read_b128 v[124:127], v204 offset:57344
	s_waitcnt lgkmcnt(1)
	v_mfma_f32_32x32x16_bf16 v[80:95], v[120:123], v[116:119], v[80:95]
	s_waitcnt lgkmcnt(0)
	v_mfma_f32_32x32x16_bf16 v[64:79], v[124:127], v[116:119], v[64:79]
	ds_read_b128 v[116:119], v202 offset:49152
	ds_read_b128 v[120:123], v202 offset:57344
	s_waitcnt lgkmcnt(1)
	v_mfma_f32_32x32x16_bf16 v[80:95], v[116:119], v[112:115], v[80:95]
	s_waitcnt lgkmcnt(0)
	v_mfma_f32_32x32x16_bf16 v[64:79], v[120:123], v[112:115], v[64:79]
	ds_read_b128 v[112:115], v191 offset:49152
	ds_read_b128 v[116:119], v191 offset:57344
	v_exp_f32_e32 v120, v150
	v_exp_f32_e32 v121, v151
	s_waitcnt lgkmcnt(1)
	v_mfma_f32_32x32x16_bf16 v[80:95], v[112:115], v[108:111], v[80:95]
	s_waitcnt lgkmcnt(0)
	v_mfma_f32_32x32x16_bf16 v[64:79], v[116:119], v[108:111], v[64:79]
	ds_read_b128 v[108:111], v203 offset:49152
	ds_read_b128 v[112:115], v203 offset:57344
	v_exp_f32_e32 v116, v158
	v_exp_f32_e32 v117, v159
	v_exp_f32_e32 v118, v152
	v_exp_f32_e32 v119, v153
	s_waitcnt lgkmcnt(1)
	v_mfma_f32_32x32x16_bf16 v[80:95], v[108:111], v[104:107], v[80:95]
	s_waitcnt lgkmcnt(0)
	v_mfma_f32_32x32x16_bf16 v[64:79], v[112:115], v[104:107], v[64:79]
	ds_read_b128 v[104:107], v206 offset:49152
	ds_read_b128 v[108:111], v206 offset:57344
	v_exp_f32_e32 v112, v146
	v_exp_f32_e32 v113, v147
	v_exp_f32_e32 v114, v144
	v_exp_f32_e32 v115, v145
	s_waitcnt lgkmcnt(1)
	v_mfma_f32_32x32x16_bf16 v[80:95], v[104:107], v[100:103], v[80:95]
	s_waitcnt lgkmcnt(0)
	v_mfma_f32_32x32x16_bf16 v[64:79], v[108:111], v[100:103], v[64:79]
	ds_read_b128 v[100:103], v207 offset:49152
	ds_read_b128 v[104:107], v207 offset:57344
	v_exp_f32_e32 v108, v154
	v_exp_f32_e32 v109, v155
	v_exp_f32_e32 v110, v148
	v_exp_f32_e32 v111, v149
	s_waitcnt lgkmcnt(1)
	v_mfma_f32_32x32x16_bf16 v[80:95], v[100:103], v[96:99], v[80:95]
	s_waitcnt lgkmcnt(0)
	v_mfma_f32_32x32x16_bf16 v[64:79], v[104:107], v[96:99], v[64:79]
	v_add_f32_e32 v96, 0, v238
	v_add_f32_e32 v96, v239, v96
	v_add_f32_e32 v96, v240, v96
	v_add_f32_e32 v96, v246, v96
	v_add_f32_e32 v96, v247, v96
	v_add_f32_e32 v96, v248, v96
	v_add_f32_e32 v96, v249, v96
	v_add_f32_e32 v96, v250, v96
	v_add_f32_e32 v96, v251, v96
	v_add_f32_e32 v96, v252, v96
	v_add_f32_e32 v96, v253, v96
	v_add_f32_e32 v96, v241, v96
	v_exp_f32_e32 v106, v156
	v_add_f32_e32 v96, v243, v96
	v_exp_f32_e32 v107, v157
	v_add_f32_e32 v96, v244, v96
	v_add_f32_e32 v96, v245, v96
	v_add_f32_e32 v96, v193, v96
	v_add_f32_e32 v96, v106, v96
	v_add_f32_e32 v96, v107, v96
	v_add_f32_e32 v96, v108, v96
	v_add_f32_e32 v96, v109, v96
	v_add_f32_e32 v96, v110, v96
	v_add_f32_e32 v96, v111, v96
	v_add_f32_e32 v96, v112, v96
	v_add_f32_e32 v96, v113, v96
	v_add_f32_e32 v96, v114, v96
	v_add_f32_e32 v96, v115, v96
	v_add_f32_e32 v96, v116, v96
	v_add_f32_e32 v96, v117, v96
	v_add_f32_e32 v96, v118, v96
	v_add_f32_e32 v96, v119, v96
	v_add_f32_e32 v96, v120, v96
	v_add_f32_e32 v96, v121, v96
	v_mov_b32_e32 v97, v96
	v_cvt_pk_bf16_f32 v98, v238, v239
	v_cvt_pk_bf16_f32 v99, v240, v246
	v_cvt_pk_bf16_f32 v100, v247, v248
	v_cvt_pk_bf16_f32 v101, v249, v250
	s_nop 1
	v_permlane32_swap_b32_e32 v96, v97
	v_permlane32_swap_b32_e32 v98, v100
	v_permlane32_swap_b32_e32 v99, v101
	v_cvt_pk_bf16_f32 v102, v251, v252
	v_cvt_pk_bf16_f32 v103, v253, v241
	v_cvt_pk_bf16_f32 v104, v243, v244
	v_cvt_pk_bf16_f32 v105, v245, v193
	v_cvt_pk_bf16_f32 v106, v106, v107
	v_cvt_pk_bf16_f32 v107, v108, v109
	v_cvt_pk_bf16_f32 v108, v110, v111
	v_cvt_pk_bf16_f32 v109, v112, v113
	v_cvt_pk_bf16_f32 v110, v114, v115
	v_cvt_pk_bf16_f32 v111, v116, v117
	v_cvt_pk_bf16_f32 v112, v118, v119
	v_cvt_pk_bf16_f32 v113, v120, v121
	s_nop 0
	v_permlane32_swap_b32_e32 v102, v104
	v_permlane32_swap_b32_e32 v103, v105
	v_permlane32_swap_b32_e32 v106, v108
	v_permlane32_swap_b32_e32 v107, v109
	v_permlane32_swap_b32_e32 v110, v112
	v_permlane32_swap_b32_e32 v111, v113
	ds_read_b64_tr_b16 v[114:115], v182 offset:0
	ds_read_b64_tr_b16 v[116:117], v182 offset:0x800
	ds_read_b64_tr_b16 v[118:119], v182 offset:0x1000
	ds_read_b64_tr_b16 v[120:121], v182 offset:0x1800
	ds_read_b64_tr_b16 v[122:123], v182 offset:0x2000
	ds_read_b64_tr_b16 v[124:125], v182 offset:0x2800
	ds_read_b64_tr_b16 v[126:127], v182 offset:0x3000
	ds_read_b64_tr_b16 v[128:129], v182 offset:0x3800
	s_waitcnt lgkmcnt(0)
	s_nop 0
	v_mfma_f32_32x32x16_bf16 v[0:15], v[98:101], v[114:117], v[0:15]
	ds_read_b64_tr_b16 v[114:115], v182 offset:0x200
	ds_read_b64_tr_b16 v[116:117], v182 offset:0xa00
	v_mfma_f32_32x32x16_bf16 v[0:15], v[102:105], v[118:121], v[0:15]
	ds_read_b64_tr_b16 v[118:119], v182 offset:0x1200
	ds_read_b64_tr_b16 v[120:121], v182 offset:0x1a00
	v_mfma_f32_32x32x16_bf16 v[0:15], v[106:109], v[122:125], v[0:15]
	ds_read_b64_tr_b16 v[122:123], v182 offset:0x2200
	ds_read_b64_tr_b16 v[124:125], v182 offset:0x2a00
	v_mfma_f32_32x32x16_bf16 v[0:15], v[110:113], v[126:129], v[0:15]
	ds_read_b64_tr_b16 v[126:127], v182 offset:0x3200
	ds_read_b64_tr_b16 v[128:129], v182 offset:0x3a00
	s_waitcnt lgkmcnt(0)
	v_mfma_f32_32x32x16_bf16 v[48:63], v[98:101], v[114:117], v[48:63]
	ds_read_b64_tr_b16 v[114:115], v182 offset:0x400
	ds_read_b64_tr_b16 v[116:117], v182 offset:0xc00
	v_mfma_f32_32x32x16_bf16 v[48:63], v[102:105], v[118:121], v[48:63]
	ds_read_b64_tr_b16 v[118:119], v182 offset:0x1400
	ds_read_b64_tr_b16 v[120:121], v182 offset:0x1c00
	v_mfma_f32_32x32x16_bf16 v[48:63], v[106:109], v[122:125], v[48:63]
	ds_read_b64_tr_b16 v[122:123], v182 offset:0x2400
	ds_read_b64_tr_b16 v[124:125], v182 offset:0x2c00
	v_mfma_f32_32x32x16_bf16 v[48:63], v[110:113], v[126:129], v[48:63]
	ds_read_b64_tr_b16 v[126:127], v182 offset:0x3400
	ds_read_b64_tr_b16 v[128:129], v182 offset:0x3c00
	s_waitcnt lgkmcnt(0)
	v_mfma_f32_32x32x16_bf16 v[32:47], v[98:101], v[114:117], v[32:47]
	ds_read_b64_tr_b16 v[114:115], v182 offset:0x600
	ds_read_b64_tr_b16 v[116:117], v182 offset:0xe00
	v_mfma_f32_32x32x16_bf16 v[32:47], v[102:105], v[118:121], v[32:47]
	ds_read_b64_tr_b16 v[118:119], v182 offset:0x1600
	ds_read_b64_tr_b16 v[120:121], v182 offset:0x1e00
	v_mfma_f32_32x32x16_bf16 v[32:47], v[106:109], v[122:125], v[32:47]
	ds_read_b64_tr_b16 v[122:123], v182 offset:0x2600
	ds_read_b64_tr_b16 v[124:125], v182 offset:0x2e00
	v_mfma_f32_32x32x16_bf16 v[32:47], v[110:113], v[126:129], v[32:47]
	ds_read_b64_tr_b16 v[126:127], v182 offset:0x3600
	ds_read_b64_tr_b16 v[128:129], v182 offset:0x3e00
	s_waitcnt lgkmcnt(0)
	v_mfma_f32_32x32x16_bf16 v[16:31], v[98:101], v[114:117], v[16:31]
	v_max_f32_e32 v98, v81, v81
	v_max_f32_e32 v99, v80, v80
	v_max_f32_e32 v98, v99, v98
	v_max3_f32 v98, v98, v82, v83
	v_max3_f32 v98, v98, v84, v85
	v_max3_f32 v98, v98, v86, v87
	v_max3_f32 v98, v98, v88, v89
	v_max3_f32 v98, v98, v90, v91
	v_max3_f32 v98, v98, v92, v93
	v_mfma_f32_32x32x16_bf16 v[16:31], v[102:105], v[118:121], v[16:31]
	v_max3_f32 v98, v98, v94, v95
	v_max3_f32 v98, v98, v64, v65
	v_max3_f32 v98, v98, v66, v67
	v_max3_f32 v98, v98, v68, v69
	v_max3_f32 v98, v98, v70, v71
	v_max3_f32 v98, v98, v72, v73
	v_max3_f32 v98, v98, v74, v75
	v_max3_f32 v98, v98, v76, v77
	v_mfma_f32_32x32x16_bf16 v[16:31], v[106:109], v[122:125], v[16:31]
	v_max3_f32 v98, v98, v78, v79
	v_mov_b32_e32 v99, v98
	s_nop 1
	v_permlane32_swap_b32_e32 v98, v99
	v_max_f32_e32 v99, v99, v99
	v_max_f32_e32 v98, v98, v98
	v_max_f32_e32 v98, v98, v99
	v_sub_f32_e32 v99, v98, v164
	v_cmp_ge_f32_e32 vcc, s85, v99
	v_max_f32_e32 v99, v164, v164
	v_max_f32_e32 v99, v99, v98
	v_mfma_f32_32x32x16_bf16 v[16:31], v[110:113], v[126:129], v[16:31]
	v_sub_f32_e32 v98, v164, v99
	v_mul_f32_e32 v98, 0x3e0293ee, v98
	v_exp_f32_e32 v98, v98
	s_cmp_eq_u64 vcc, exec
	s_cselect_b64 s[42:43], -1, 0
	v_cndmask_b32_e64 v98, v98, 1.0, s[42:43]
	v_cmp_gt_f32_e32 vcc, 1.0, v98
	s_barrier
	s_cbranch_vccz .LBB0_742
	s_and_saveexec_b64 s[2:3], s[40:41]
	ds_write_b32 v185, v98 offset:128
	s_or_b64 exec, exec, s[2:3]
	s_waitcnt lgkmcnt(0)
	v_add_u32_e32 v112, v177, v194
	ds_read_b128 v[100:103], v112 offset:224
	ds_read_b128 v[104:107], v112 offset:192
	ds_read_b128 v[108:111], v112 offset:160
	ds_read_b128 v[112:115], v112 offset:128
	s_waitcnt lgkmcnt(3)
	v_pk_mul_f32 v[12:13], v[12:13], v[100:101]
	s_waitcnt lgkmcnt(2)
	v_pk_mul_f32 v[8:9], v[8:9], v[104:105]
	s_waitcnt lgkmcnt(1)
	v_pk_mul_f32 v[4:5], v[4:5], v[108:109]
	v_pk_mul_f32 v[14:15], v[14:15], v[102:103]
	v_pk_mul_f32 v[10:11], v[10:11], v[106:107]
	v_pk_mul_f32 v[6:7], v[6:7], v[110:111]
	s_waitcnt lgkmcnt(0)
	v_pk_mul_f32 v[2:3], v[2:3], v[114:115]
	v_pk_mul_f32 v[0:1], v[0:1], v[112:113]
	v_pk_mul_f32 v[60:61], v[60:61], v[100:101]
	v_pk_mul_f32 v[56:57], v[56:57], v[104:105]
	v_pk_mul_f32 v[52:53], v[52:53], v[108:109]
	v_pk_mul_f32 v[62:63], v[62:63], v[102:103]
	v_pk_mul_f32 v[58:59], v[58:59], v[106:107]
	v_pk_mul_f32 v[54:55], v[54:55], v[110:111]
	v_pk_mul_f32 v[50:51], v[50:51], v[114:115]
	v_pk_mul_f32 v[48:49], v[48:49], v[112:113]
	v_pk_mul_f32 v[44:45], v[44:45], v[100:101]
	v_pk_mul_f32 v[40:41], v[40:41], v[104:105]
	v_pk_mul_f32 v[36:37], v[36:37], v[108:109]
	v_pk_mul_f32 v[46:47], v[46:47], v[102:103]
	v_pk_mul_f32 v[42:43], v[42:43], v[106:107]
	v_pk_mul_f32 v[38:39], v[38:39], v[110:111]
	v_pk_mul_f32 v[34:35], v[34:35], v[114:115]
	v_pk_mul_f32 v[32:33], v[32:33], v[112:113]
	v_pk_mul_f32 v[28:29], v[28:29], v[100:101]
	v_pk_mul_f32 v[24:25], v[24:25], v[104:105]
	v_pk_mul_f32 v[20:21], v[20:21], v[108:109]
	v_pk_mul_f32 v[30:31], v[30:31], v[102:103]
	v_pk_mul_f32 v[26:27], v[26:27], v[106:107]
	v_pk_mul_f32 v[22:23], v[22:23], v[110:111]
	v_pk_mul_f32 v[18:19], v[18:19], v[114:115]
	v_pk_mul_f32 v[16:17], v[16:17], v[112:113]
